# out-proj/ff2 tile prologue: K-slice 1 requested before waiting for K-slice 0 (prologue wait+barrier moved behind the pre-loop block's DMA issue, counted vmcnt(8)); on v195
# baseline (speedup 1.0000x reference)
; #define WAIT_V0() asm volatile("s_waitcnt vmcnt(0)" ::: "memory")
; #define G_LANE_SETUP() \
;     int tid_ = threadIdx.x; \
;     asm volatile("" : "+v"(tid_));    \
;     const int wid = tid_ >> 6, lane = tid_ & 63, wr = wid >> 2, wc = wid & 3, fr = lane & 15, fq = lane >> 4; \
;     unsigned soff[4];        \
;     _Pragma("unroll") for (int i = 0; i < 4; ++i) { int sR, sC; stage_rc2(wid * 1024 + i * 8192 + lane * 16, sR, sC); soff[i] = (unsigned)(sR * K + sC) * 2u; }
; template <int EK>
; DI void gemm_stream(const Params& p, int l, const bf16_t* __restrict__ A, const bf16_t* __restrict__ Bt, int M, int N, int K, ldsp_t shm) {
;     ...
;     const int nt = K / 64;
;     int pm, pn;
;     tile_coords(L, nM, nN, pm, pn);
;     const bf16_t* Ab = A + (size_t)pm * 256 * K;
;     const bf16_t* Bb = Bt + (size_t)pn * 256 * K;
;     { G_LANE_SETUP(); (void)wr; (void)wc; (void)fr; (void)fq; G_STAGE(Ab, Bb, 0, 0); WAIT_V0(); __syncthreads(); }
.LBB0_122:
	v_readlane_b32 s4, v255, 10
	v_readlane_b32 s5, v255, 11
	s_ashr_i32 s5, s4, 31
	v_writelane_b32 v255, s4, 10
	s_lshl_b64 s[6:7], s[4:5], 21
	v_readlane_b32 s24, v254, 23
	v_writelane_b32 v255, s5, 11
	v_readlane_b32 s4, v253, 28
	s_add_u32 s93, s58, s6
	v_readlane_b32 s5, v253, 29
	v_readlane_b32 s25, v254, 24
	s_mov_b64 s[48:49], s[88:89]
	s_addc_u32 s98, s59, s7
	s_andn2_b64 vcc, exec, s[4:5]
	v_readlane_b32 s26, v254, 25
	v_readlane_b32 s27, v254, 26
	v_readlane_b32 s24, v254, 22
	v_readlane_b32 s25, v254, 27
	s_cbranch_vccnz .LBB0_153
	v_mov_b32_e32 v0, v252
	s_mov_b32 s4, 0x1ffff0
	v_lshlrev_b32_e32 v1, 4, v0
	v_and_b32_e32 v3, 32, v0
	v_and_b32_e32 v2, 0xfffffc00, v1
	v_bitop3_b32 v3, v1, v3, 48 bitop3:0x6c
	s_waitcnt lgkmcnt(0)
	v_add_u32_e32 v5, 0x2000, v1
	v_add_u32_e32 v6, 0x4000, v1
	v_add_u32_e32 v1, 0x6000, v1
	v_bfe_u32 v4, v0, 2, 4
	v_and_or_b32 v3, v0, 64, v3
	v_lshrrev_b32_e32 v0, 3, v0
	v_lshrrev_b32_e32 v5, 7, v5
	v_lshrrev_b32_e32 v6, 7, v6
	v_lshrrev_b32_e32 v1, 7, v1
	v_and_or_b32 v0, v0, s4, v4
	v_and_or_b32 v5, v5, s4, v4
	v_and_or_b32 v6, v6, s4, v4
	v_and_or_b32 v1, v1, s4, v4
	v_lshl_or_b32 v0, v0, 11, v3
	v_lshl_or_b32 v5, v5, 11, v3
	v_lshl_or_b32 v6, v6, 11, v3
	v_lshl_or_b32 v1, v1, 11, v3
	v_readlane_b32 s46, v253, 52
	v_add_u32_e32 v3, 0x8000, v2
	v_readfirstlane_b32 s31, v2
	v_readlane_b32 s8, v253, 56
	v_readlane_b32 s47, v253, 53
	s_add_u32 s4, s93, s46
	s_mov_b32 m0, s31
	v_readlane_b32 s9, v253, 57
	v_readfirstlane_b32 s31, v3
	s_addc_u32 s5, s98, s47
	v_readlane_b32 s50, v253, 54
	v_readlane_b32 s87, v253, 58
	v_readlane_b32 s51, v253, 55
	global_load_lds_dwordx4 v0, s[8:9]
	s_mov_b32 m0, s31
	v_readlane_b32 s86, v253, 0
	global_load_lds_dwordx4 v0, s[4:5]
	v_add_u32_e32 v0, 0x2000, v2
	s_nop 0
	v_readfirstlane_b32 s31, v0
	v_add_u32_e32 v0, 0xa000, v2
	s_mov_b32 m0, s31
	v_readfirstlane_b32 s31, v0
	v_add_u32_e32 v0, 0x4000, v2
	global_load_lds_dwordx4 v5, s[8:9]
	s_mov_b32 m0, s31
	v_readfirstlane_b32 s31, v0
	v_add_u32_e32 v0, 0xc000, v2
	global_load_lds_dwordx4 v5, s[4:5]
	s_mov_b32 m0, s31
	v_readfirstlane_b32 s31, v0
	v_add_u32_e32 v0, 0x6000, v2
	global_load_lds_dwordx4 v6, s[8:9]
	s_mov_b32 m0, s31
	v_readfirstlane_b32 s31, v0
	v_add_u32_e32 v0, 0xe000, v2
	global_load_lds_dwordx4 v6, s[4:5]
	s_mov_b32 m0, s31
	v_readfirstlane_b32 s31, v0
	global_load_lds_dwordx4 v1, s[8:9]
	s_mov_b32 m0, s31
	v_readlane_b32 s8, v253, 3
	global_load_lds_dwordx4 v1, s[4:5]
	v_readlane_b32 s4, v255, 10
	v_readlane_b32 s5, v255, 11
	s_lshl_b64 s[34:35], s[4:5], 12
	s_lshl_b32 s4, s4, 1
	s_or_b32 s4, s4, 1
	s_mul_hi_i32 s36, s4, 0x110000
	s_mul_i32 s31, s4, 0x110000
	v_readlane_b32 s4, v255, 9
	s_add_i32 s4, s4, 2
	s_cmp_lt_u32 s4, 9
	v_readlane_b32 s20, v253, 15
	s_cselect_b64 s[4:5], -1, 0
	v_readlane_b32 s21, v253, 16
	s_add_u32 s34, s20, s34
	s_addc_u32 s35, s21, s35
	s_add_u32 s31, s74, s31
	s_addc_u32 s45, s75, s36
	v_readlane_b32 s8, v254, 20
	s_nop 0
	s_add_u32 s84, s8, s6
	v_readlane_b32 s6, v254, 21
	s_addc_u32 s85, s6, s7
	v_readlane_b32 s6, v253, 63
	s_mov_b32 s88, s6
	s_waitcnt lgkmcnt(0)
	s_nop 0
	v_readlane_b32 s9, v253, 4
	v_readlane_b32 s10, v253, 5
	v_readlane_b32 s11, v253, 6
	v_readlane_b32 s12, v253, 7
	v_readlane_b32 s13, v253, 8
	v_readlane_b32 s14, v253, 9
	v_readlane_b32 s15, v253, 10
	v_readlane_b32 s16, v253, 11
	v_readlane_b32 s17, v253, 12
	v_readlane_b32 s18, v253, 13
	v_readlane_b32 s19, v253, 14
	v_readlane_b32 s22, v253, 17
	v_readlane_b32 s23, v253, 18
	v_readlane_b32 s7, v254, 0
	s_branch .LBB0_125

; #define G_LANE_SETUP() \
;     int tid_ = threadIdx.x; \
;     asm volatile("" : "+v"(tid_));    \
;     const int wid = tid_ >> 6, lane = tid_ & 63, wr = wid >> 2, wc = wid & 3, fr = lane & 15, fq = lane >> 4; \
;     unsigned soff[4];        \
;     _Pragma("unroll") for (int i = 0; i < 4; ++i) { int sR, sC; stage_rc2(wid * 1024 + i * 8192 + lane * 16, sR, sC); soff[i] = (unsigned)(sR * K + sC) * 2u; }
; #define G_STAGE_A(Ap, buf, kt) do { const char* ab_ = (const char*)(Ap) + (size_t)(kt) * 128; \
;       _Pragma("unroll") for (int i = 0; i < 4; ++i) \
;         __builtin_amdgcn_global_load_lds((const unsigned*)(ab_ + soff[i]), (LDSP unsigned*)(G_SA(buf) + wid * 1024 + i * 8192), 16, 0, 0); } while (0)
; #define G_STAGE_B(Bp, buf, kt) do { const char* bb_ = (const char*)(Bp) + (size_t)(kt) * 128; \
;       _Pragma("unroll") for (int i = 0; i < 4; ++i) \
;         __builtin_amdgcn_global_load_lds((const unsigned*)(bb_ + soff[i]), (LDSP unsigned*)(G_SB(buf) + wid * 1024 + i * 8192), 16, 0, 0); } while (0)
; #define G_SB0() __builtin_amdgcn_sched_barrier(0)
; template <int EK>
; DI void gemm_stream(const Params& p, int l, const bf16_t* __restrict__ A, const bf16_t* __restrict__ Bt, int M, int N, int K, ldsp_t shm) {
;     ...
;         G_LANE_SETUP();
;         const int aoff = lds_byte2(wr * 128 + fr, fq * 8), boff = lds_byte2(wc * 64 + fr, fq * 8);
;         f32x4 acc[8][4];
; #pragma unroll
;         for (int m = 0; m < 8; ++m)
; #pragma unroll
;             for (int n = 0; n < 4; ++n) acc[m][n] = (f32x4){0.f, 0.f, 0.f, 0.f};
;         const int Ln = L + gridDim.x;
;         const bool has_next = Ln < nwg;
;         int pm2 = pm, pn2 = pn;
;         if (has_next) tile_coords(Ln, nM, nN, pm2, pn2);
;         const bf16_t* Ab2 = A + (size_t)pm2 * 256 * K;
;         const bf16_t* Bb2 = Bt + (size_t)pn2 * 256 * K;
;         bf16x8 Aa[4], Ab_[4], Bk0[4], Bk1[4];
;     ...
;         for (int t = 0; t < nt; ++t) {
;             const int cur = t & 1;
;             G_RDA(Aa, cur, 0, 0); G_RDB(Bk0, cur, 0);
;             if (t + 1 < nt) G_STAGE_B(Bb, cur ^ 1, t + 1);
;             else if (has_next) G_STAGE_B(Bb2, cur ^ 1, 0);
;             G_SB0();
;             if (t > 0) G_MMA(Ab_, Bk1, 1);
;             G_SB0();
;             if (t + 1 < nt) G_STAGE_A(Ab, cur ^ 1, t + 1);
;             else if (has_next) G_STAGE_A(Ab2, cur ^ 1, 0);
.LBB0_131:
	v_lshlrev_b32_e32 v0, 4, v160
	v_and_b32_e32 v1, 32, v160
	v_bfe_u32 v161, v160, 2, 4
	v_and_b32_e32 v190, 64, v160
	v_bitop3_b32 v191, v0, v1, 48 bitop3:0x6c
	v_lshrrev_b32_e32 v2, 3, v160
	s_mov_b32 s6, 0x1ffff0
	v_or_b32_e32 v1, v191, v190
	v_and_or_b32 v2, v2, s6, v161
	v_add_u32_e32 v200, 0x2000, v0
	v_lshl_or_b32 v192, v2, 11, v1
	v_lshrrev_b32_e32 v2, 7, v200
	v_and_or_b32 v2, v2, s6, v161
	v_add_u32_e32 v201, 0x4000, v0
	v_add_u32_e32 v221, 0x6000, v0
	v_and_b32_e32 v220, 0xfffffc00, v0
	v_lshl_or_b32 v194, v2, 11, v1
	v_lshrrev_b32_e32 v2, 7, v201
	v_lshrrev_b32_e32 v0, 7, v221
	v_and_or_b32 v2, v2, s6, v161
	v_and_or_b32 v0, v0, s6, v161
	v_lshl_or_b32 v196, v2, 11, v1
	v_lshl_or_b32 v198, v0, 11, v1
	v_lshlrev_b32_e32 v1, 6, v160
	v_lshlrev_b32_e32 v4, 2, v160
	v_and_b32_e32 v0, 48, v160
	v_and_b32_e32 v2, 0x3c0, v1
	v_and_b32_e32 v4, 32, v4
	v_bitop3_b32 v0, v2, v4, v0 bitop3:0x36
	s_movk_i32 s6, 0xc000
	v_and_or_b32 v218, v1, s6, v0
	s_add_u32 s6, s93, s46
	s_addc_u32 s7, s98, s47
	v_add_u32_e32 v34, 0x18000, v220
	v_lshl_add_u64 v[32:33], s[6:7], 0, v[192:193]
	v_readfirstlane_b32 s41, v34
	v_lshlrev_b32_e32 v3, 7, v160
	v_lshl_add_u64 v[32:33], v[32:33], 0, s[0:1]
	s_mov_b32 m0, s41
	v_mov_b32_e32 v195, v193
	v_add_u32_e32 v34, 0x1a000, v220
	v_and_or_b32 v219, v3, s28, v0
	global_load_lds_dwordx4 v[32:33], off
	v_lshl_add_u64 v[32:33], s[6:7], 0, v[194:195]
	v_readfirstlane_b32 s41, v34
	v_lshl_add_u64 v[32:33], v[32:33], 0, s[0:1]
	s_mov_b32 m0, s41
	v_mov_b32_e32 v197, v193
	v_add_u32_e32 v34, 0x1c000, v220
	global_load_lds_dwordx4 v[32:33], off
	v_lshl_add_u64 v[32:33], s[6:7], 0, v[196:197]
	v_readfirstlane_b32 s41, v34
	v_lshl_add_u64 v[32:33], v[32:33], 0, s[0:1]
	s_mov_b32 m0, s41
	v_mov_b32_e32 v199, v193
	v_add_u32_e32 v34, 0x1e000, v220
	global_load_lds_dwordx4 v[32:33], off
	v_lshl_add_u64 v[32:33], s[6:7], 0, v[198:199]
	v_readfirstlane_b32 s6, v34
	v_lshl_add_u64 v[32:33], v[32:33], 0, s[0:1]
	s_mov_b32 m0, s6
	s_nop 0
	global_load_lds_dwordx4 v[32:33], off
	s_add_u32 s6, s26, s50
	s_addc_u32 s7, s27, s51
	v_add_u32_e32 v34, 0x10000, v220
	v_lshl_add_u64 v[32:33], s[6:7], 0, v[192:193]
	v_readfirstlane_b32 s41, v34
	v_lshl_add_u64 v[32:33], v[32:33], 0, s[0:1]
	s_mov_b32 m0, s41
	v_add_u32_e32 v34, 0x12000, v220
	global_load_lds_dwordx4 v[32:33], off
	v_lshl_add_u64 v[32:33], s[6:7], 0, v[194:195]
	v_readfirstlane_b32 s41, v34
	v_lshl_add_u64 v[32:33], v[32:33], 0, s[0:1]
	s_mov_b32 m0, s41
	v_add_u32_e32 v34, 0x14000, v220
	global_load_lds_dwordx4 v[32:33], off
	v_lshl_add_u64 v[32:33], s[6:7], 0, v[196:197]
	v_readfirstlane_b32 s41, v34
	v_lshl_add_u64 v[32:33], v[32:33], 0, s[0:1]
	s_mov_b32 m0, s41
	v_add_u32_e32 v34, 0x16000, v220
	global_load_lds_dwordx4 v[32:33], off
	v_lshl_add_u64 v[32:33], s[6:7], 0, v[198:199]
	v_readfirstlane_b32 s6, v34
	v_lshl_add_u64 v[32:33], v[32:33], 0, s[0:1]
	s_mov_b32 m0, s6
	s_mov_b32 s41, 0x10000
	global_load_lds_dwordx4 v[32:33], off
	s_waitcnt vmcnt(8)
	s_barrier
; #define WAIT_V0() asm volatile("s_waitcnt vmcnt(0)" ::: "memory")
; #define G_STAGE_A(Ap, buf, kt) do { const char* ab_ = (const char*)(Ap) + (size_t)(kt) * 128; \
;       _Pragma("unroll") for (int i = 0; i < 4; ++i) \
;         __builtin_amdgcn_global_load_lds((const unsigned*)(ab_ + soff[i]), (LDSP unsigned*)(G_SA(buf) + wid * 1024 + i * 8192), 16, 0, 0); } while (0)
; #define G_STAGE_B(Bp, buf, kt) do { const char* bb_ = (const char*)(Bp) + (size_t)(kt) * 128; \
;       _Pragma("unroll") for (int i = 0; i < 4; ++i) \
;         __builtin_amdgcn_global_load_lds((const unsigned*)(bb_ + soff[i]), (LDSP unsigned*)(G_SB(buf) + wid * 1024 + i * 8192), 16, 0, 0); } while (0)
; #define G_RDA(AF, buf, ks, mh) do { _Pragma("unroll") for (int m = 0; m < 4; ++m) AF[m] = *(const LDSP bf16x8*)(G_SA(buf) + aoff + ((mh) * 4 + m) * 2048 + (ks) * 1024); } while (0)
; #define G_RDB(BF, buf, ks) do { _Pragma("unroll") for (int n = 0; n < 4; ++n) BF[n] = *(const LDSP bf16x8*)(G_SB(buf) + boff + n * 2048 + (ks) * 1024); } while (0)
; #define G_MMA(AF, BF, mh) do { __builtin_amdgcn_s_setprio(1); \
;             _Pragma("unroll") for (int m = 0; m < 4; ++m) _Pragma("unroll") for (int n = 0; n < 4; ++n) \
;                 acc[(mh) * 4 + m][n] = __builtin_amdgcn_mfma_f32_16x16x32_bf16(BF[n], AF[m], acc[(mh) * 4 + m][n], 0, 0, 0); \
;             __builtin_amdgcn_s_setprio(0); } while (0)
; template <int EK>
; DI void gemm_stream(const Params& p, int l, const bf16_t* __restrict__ A, const bf16_t* __restrict__ Bt, int M, int N, int K, ldsp_t shm) {
;     ...
;         for (int t = 0; t < nt; ++t) {
;             const int cur = t & 1;
;             G_RDA(Aa, cur, 0, 0); G_RDB(Bk0, cur, 0);
;             if (t + 1 < nt) G_STAGE_B(Bb, cur ^ 1, t + 1);
;             else if (has_next) G_STAGE_B(Bb2, cur ^ 1, 0);
;             G_SB0();
;             if (t > 0) G_MMA(Ab_, Bk1, 1);
;             G_SB0();
;             if (t + 1 < nt) G_STAGE_A(Ab, cur ^ 1, t + 1);
;             else if (has_next) G_STAGE_A(Ab2, cur ^ 1, 0);
;             G_RDA(Ab_, cur, 0, 1);
;             G_MMA(Aa, Bk0, 0); G_SB0();
;             G_RDA(Aa, cur, 1, 0); G_RDB(Bk1, cur, 1);
;             G_MMA(Ab_, Bk0, 1); G_SB0();
;             G_RDA(Ab_, cur, 1, 1);
;             G_MMA(Aa, Bk1, 0); G_SB0();
;             asm volatile("s_waitcnt lgkmcnt(0)" ::: "memory");
;             WAIT_V0(); __syncthreads();
	ds_read_b128 v[0:3], v218
	ds_read_b128 v[4:7], v218 offset:2048
	ds_read_b128 v[8:11], v218 offset:4096
	ds_read_b128 v[12:15], v218 offset:6144
	ds_read_b128 v[16:19], v219 offset:32768
	ds_read_b128 v[20:23], v219 offset:34816
	ds_read_b128 v[24:27], v219 offset:36864
	ds_read_b128 v[28:31], v219 offset:38912
	ds_read_b128 v[32:35], v218 offset:8192
	ds_read_b128 v[36:39], v218 offset:10240
	ds_read_b128 v[40:43], v218 offset:12288
	ds_read_b128 v[44:47], v218 offset:14336
	s_setprio 1
	s_waitcnt lgkmcnt(0)
	v_mfma_f32_16x16x32_bf16 v[48:51], v[16:19], v[0:3], 0
	v_mfma_f32_16x16x32_bf16 v[52:55], v[20:23], v[0:3], 0
	v_mfma_f32_16x16x32_bf16 v[56:59], v[24:27], v[0:3], 0
	v_mfma_f32_16x16x32_bf16 v[60:63], v[28:31], v[0:3], 0
	v_mfma_f32_16x16x32_bf16 v[162:165], v[16:19], v[4:7], 0
	v_mfma_f32_16x16x32_bf16 v[166:169], v[20:23], v[4:7], 0
	v_mfma_f32_16x16x32_bf16 v[170:173], v[24:27], v[4:7], 0
	v_mfma_f32_16x16x32_bf16 v[174:177], v[28:31], v[4:7], 0
	v_mfma_f32_16x16x32_bf16 v[178:181], v[16:19], v[8:11], 0
	v_mfma_f32_16x16x32_bf16 v[182:185], v[20:23], v[8:11], 0
	v_mfma_f32_16x16x32_bf16 v[186:189], v[24:27], v[8:11], 0
	v_mfma_f32_16x16x32_bf16 v[204:207], v[28:31], v[8:11], 0
	v_mfma_f32_16x16x32_bf16 v[210:213], v[16:19], v[12:15], 0
	v_mfma_f32_16x16x32_bf16 v[214:217], v[20:23], v[12:15], 0
	v_mfma_f32_16x16x32_bf16 v[222:225], v[24:27], v[12:15], 0
	v_mfma_f32_16x16x32_bf16 v[226:229], v[28:31], v[12:15], 0
	s_setprio 0
	ds_read_b128 v[12:15], v218 offset:1024
	ds_read_b128 v[230:233], v218 offset:3072
	ds_read_b128 v[234:237], v218 offset:5120
	ds_read_b128 v[238:241], v218 offset:7168
	ds_read_b128 v[64:67], v219 offset:33792
	ds_read_b128 v[68:71], v219 offset:35840
	ds_read_b128 v[72:75], v219 offset:37888
	ds_read_b128 v[76:79], v219 offset:39936
	s_setprio 1
	v_mfma_f32_16x16x32_bf16 v[140:143], v[16:19], v[32:35], 0
	v_mfma_f32_16x16x32_bf16 v[136:139], v[20:23], v[32:35], 0
	v_mfma_f32_16x16x32_bf16 v[132:135], v[24:27], v[32:35], 0
	v_mfma_f32_16x16x32_bf16 v[128:131], v[28:31], v[32:35], 0
	v_mfma_f32_16x16x32_bf16 v[124:127], v[16:19], v[36:39], 0
	v_mfma_f32_16x16x32_bf16 v[120:123], v[20:23], v[36:39], 0
	v_mfma_f32_16x16x32_bf16 v[116:119], v[24:27], v[36:39], 0
	v_mfma_f32_16x16x32_bf16 v[112:115], v[28:31], v[36:39], 0
	v_mfma_f32_16x16x32_bf16 v[108:111], v[16:19], v[40:43], 0
	v_mfma_f32_16x16x32_bf16 v[104:107], v[20:23], v[40:43], 0
	v_mfma_f32_16x16x32_bf16 v[100:103], v[24:27], v[40:43], 0
	v_mfma_f32_16x16x32_bf16 v[96:99], v[28:31], v[40:43], 0
	v_mfma_f32_16x16x32_bf16 v[92:95], v[16:19], v[44:47], 0
	v_mfma_f32_16x16x32_bf16 v[88:91], v[20:23], v[44:47], 0
	v_mfma_f32_16x16x32_bf16 v[84:87], v[24:27], v[44:47], 0
	v_mfma_f32_16x16x32_bf16 v[80:83], v[28:31], v[44:47], 0
	s_setprio 0
	ds_read_b128 v[156:159], v218 offset:9216
	ds_read_b128 v[152:155], v218 offset:11264
	ds_read_b128 v[148:151], v218 offset:13312
	ds_read_b128 v[144:147], v218 offset:15360
	s_setprio 1
	s_waitcnt lgkmcnt(0)
	v_mfma_f32_16x16x32_bf16 v[0:3], v[64:67], v[12:15], v[48:51]
	v_mfma_f32_16x16x32_bf16 v[4:7], v[68:71], v[12:15], v[52:55]
	v_mfma_f32_16x16x32_bf16 v[8:11], v[72:75], v[12:15], v[56:59]
	v_mfma_f32_16x16x32_bf16 v[12:15], v[76:79], v[12:15], v[60:63]
	v_mfma_f32_16x16x32_bf16 v[16:19], v[64:67], v[230:233], v[162:165]
	v_mfma_f32_16x16x32_bf16 v[20:23], v[68:71], v[230:233], v[166:169]
	v_mfma_f32_16x16x32_bf16 v[24:27], v[72:75], v[230:233], v[170:173]
	v_mfma_f32_16x16x32_bf16 v[28:31], v[76:79], v[230:233], v[174:177]
	v_mfma_f32_16x16x32_bf16 v[32:35], v[64:67], v[234:237], v[178:181]
	v_mfma_f32_16x16x32_bf16 v[36:39], v[68:71], v[234:237], v[182:185]
	v_mfma_f32_16x16x32_bf16 v[40:43], v[72:75], v[234:237], v[186:189]
	v_mfma_f32_16x16x32_bf16 v[44:47], v[76:79], v[234:237], v[204:207]
	v_mfma_f32_16x16x32_bf16 v[48:51], v[64:67], v[238:241], v[210:213]
	v_mfma_f32_16x16x32_bf16 v[52:55], v[68:71], v[238:241], v[214:217]
	v_mfma_f32_16x16x32_bf16 v[56:59], v[72:75], v[238:241], v[222:225]
	v_mfma_f32_16x16x32_bf16 v[60:63], v[76:79], v[238:241], v[226:229]
	s_setprio 0
	v_lshlrev_b32_e32 v160, 8, v160
	v_lshlrev_b32_e32 v162, 4, v200
	v_lshlrev_b32_e32 v164, 4, v201
	v_lshlrev_b32_e32 v167, 4, v221
	v_and_or_b32 v160, v160, s90, v191
	v_lshlrev_b32_e32 v166, 11, v161
	s_add_u32 s6, s84, s46
	v_and_or_b32 v162, v162, s90, v191
	v_and_or_b32 v164, v164, s90, v191
	v_and_or_b32 v167, v167, s90, v191
	s_waitcnt lgkmcnt(0)
	v_or3_b32 v168, v160, v166, v190
	v_mov_b32_e32 v169, v193
	s_addc_u32 s7, s85, s47
	v_or3_b32 v170, v162, v166, v190
	v_mov_b32_e32 v171, v193
	v_or3_b32 v172, v164, v166, v190
	v_mov_b32_e32 v173, v193
	v_or3_b32 v174, v167, v166, v190
	v_mov_b32_e32 v175, v193
	s_waitcnt vmcnt(0)
	v_writelane_b32 v255, s52, 12
	v_writelane_b32 v255, s53, 13
	v_writelane_b32 v255, s64, 14
	v_writelane_b32 v255, s65, 15
	v_writelane_b32 v255, s30, 16
	s_mov_b64 s[64:65], s[6:7]
	s_add_u32 s6, s24, s50
	s_addc_u32 s7, s25, s51
	s_mov_b64 s[52:53], s[6:7]
	s_mov_b64 s[6:7], 0
	s_waitcnt vmcnt(0)
	v_lshrrev_b32_e32 v164, 6, v252
	v_lshlrev_b32_e32 v164, 10, v164
	s_nop 0
	v_readfirstlane_b32 s30, v164
	v_and_b32_e32 v165, 63, v252
	v_lshlrev_b32_e32 v165, 4, v165
	s_barrier
	s_and_b32 s43, s41, 0x10000
	v_add_u32_e32 v221, s43, v218
	v_or_b32_e32 v226, s43, v219
	s_xor_b32 s43, s43, 0x10000
	s_add_u32 s43, s43, s30
	.p2align	6

; #define WAIT_V0() asm volatile("s_waitcnt vmcnt(0)" ::: "memory")
; #define G_LANE_SETUP() \
;     int tid_ = threadIdx.x; \
;     asm volatile("" : "+v"(tid_));    \
;     const int wid = tid_ >> 6, lane = tid_ & 63, wr = wid >> 2, wc = wid & 3, fr = lane & 15, fq = lane >> 4; \
;     unsigned soff[4];        \
;     _Pragma("unroll") for (int i = 0; i < 4; ++i) { int sR, sC; stage_rc2(wid * 1024 + i * 8192 + lane * 16, sR, sC); soff[i] = (unsigned)(sR * K + sC) * 2u; }
; template <int EK>
; DI void gemm_stream(const Params& p, int l, const bf16_t* __restrict__ A, const bf16_t* __restrict__ Bt, int M, int N, int K, ldsp_t shm) {
;     ...
;     const int nt = K / 64;
;     int pm, pn;
;     tile_coords(L, nM, nN, pm, pn);
;     const bf16_t* Ab = A + (size_t)pm * 256 * K;
;     const bf16_t* Bb = Bt + (size_t)pn * 256 * K;
;     { G_LANE_SETUP(); (void)wr; (void)wc; (void)fr; (void)fq; G_STAGE(Ab, Bb, 0, 0); WAIT_V0(); __syncthreads(); }
.LBB0_179:
	v_readlane_b32 s8, v255, 7
	v_readlane_b32 s9, v255, 8
	s_and_b64 vcc, exec, s[8:9]
	s_cbranch_vccz .LBB0_251
	s_ashr_i32 s49, s48, 31
	s_lshl_b64 s[4:5], s[48:49], 23
	s_add_u32 s9, s62, s4
	v_writelane_b32 v255, s4, 10
	s_addc_u32 s31, s63, s5
	s_nop 0
	v_writelane_b32 v255, s5, 11
	v_readlane_b32 s4, v253, 28
	v_readlane_b32 s5, v253, 29
	s_andn2_b64 vcc, exec, s[4:5]
	s_cbranch_vccnz .LBB0_243
	v_mov_b32_e32 v0, v252
	v_readlane_b32 s50, v254, 1
	v_lshlrev_b32_e32 v1, 4, v0
	v_and_b32_e32 v3, 32, v0
	v_and_b32_e32 v2, 0xfffffc00, v1
	v_bitop3_b32 v3, v1, v3, 48 bitop3:0x6c
	s_waitcnt lgkmcnt(0)
	v_add_u32_e32 v5, 0x2000, v1
	v_add_u32_e32 v6, 0x4000, v1
	v_add_u32_e32 v1, 0x6000, v1
	v_bfe_u32 v4, v0, 2, 4
	v_and_or_b32 v3, v0, 64, v3
	v_lshrrev_b32_e32 v0, 3, v0
	v_lshrrev_b32_e32 v5, 7, v5
	v_lshrrev_b32_e32 v6, 7, v6
	v_lshrrev_b32_e32 v1, 7, v1
	v_and_or_b32 v0, v0, s6, v4
	v_and_or_b32 v5, v5, s6, v4
	v_and_or_b32 v6, v6, s6, v4
	v_and_or_b32 v1, v1, s6, v4
	v_lshl_or_b32 v0, v0, 13, v3
	v_lshl_or_b32 v5, v5, 13, v3
	v_lshl_or_b32 v6, v6, 13, v3
	v_lshl_or_b32 v1, v1, 13, v3
	v_add_u32_e32 v3, 0x8000, v2
	v_readfirstlane_b32 s6, v2
	v_readlane_b32 s10, v254, 5
	v_readlane_b32 s51, v254, 2
	s_add_u32 s4, s9, s50
	s_mov_b32 m0, s6
	v_readlane_b32 s11, v254, 6
	v_readfirstlane_b32 s6, v3
	s_addc_u32 s5, s31, s51
	v_readlane_b32 s12, v254, 50
	v_readlane_b32 s24, v254, 62
	v_readlane_b32 s25, v254, 63
	global_load_lds_dwordx4 v0, s[10:11]
	s_mov_b32 m0, s6
	v_readlane_b32 s16, v254, 54
	global_load_lds_dwordx4 v0, s[4:5]
	v_add_u32_e32 v0, 0x2000, v2
	v_readlane_b32 s17, v254, 55
	v_readfirstlane_b32 s6, v0
	v_add_u32_e32 v0, 0xa000, v2
	s_mov_b32 m0, s6
	v_readfirstlane_b32 s6, v0
	v_add_u32_e32 v0, 0x4000, v2
	global_load_lds_dwordx4 v5, s[10:11]
	s_mov_b32 m0, s6
	v_readfirstlane_b32 s6, v0
	v_add_u32_e32 v0, 0xc000, v2
	global_load_lds_dwordx4 v5, s[4:5]
	s_mov_b32 m0, s6
	v_readfirstlane_b32 s6, v0
	v_add_u32_e32 v0, 0x6000, v2
	global_load_lds_dwordx4 v6, s[10:11]
	s_mov_b32 m0, s6
	v_readfirstlane_b32 s6, v0
	v_add_u32_e32 v0, 0xe000, v2
	global_load_lds_dwordx4 v6, s[4:5]
	s_mov_b32 m0, s6
	v_readfirstlane_b32 s6, v0
	global_load_lds_dwordx4 v1, s[10:11]
	s_mov_b32 m0, s6
	v_readlane_b32 s18, v254, 56
	global_load_lds_dwordx4 v1, s[4:5]
	v_readlane_b32 s4, v255, 9
	s_cmp_gt_i32 s4, 16
	s_cselect_b64 s[36:37], -1, 0
	s_cmp_lt_i32 s4, 17
	s_cselect_b64 s[4:5], -1, 0
	s_cmp_lg_u64 s[4:5], 0
	s_addc_u32 s4, s48, 0
	s_ashr_i32 s5, s4, 31
	s_lshl_b64 s[6:7], s[4:5], 12
	s_lshl_b32 s5, s4, 1
	s_add_u32 s38, s24, s6
	s_mul_hi_i32 s93, s4, 5
	s_mul_i32 s98, s4, 5
	s_mul_i32 s4, s4, 0x220000
	s_addc_u32 s39, s25, s7
	s_mul_hi_i32 s5, s5, 0x110000
	v_readlane_b32 s19, v254, 57
	s_add_u32 s10, s74, s4
	v_readlane_b32 s16, v254, 23
	s_addc_u32 s11, s75, s5
	v_readlane_b32 s4, v254, 40
	v_readlane_b32 s6, v255, 10
	s_nop 0
	v_readlane_b32 s13, v254, 51
	v_readlane_b32 s20, v254, 58
	v_readlane_b32 s21, v254, 59
	v_readlane_b32 s22, v254, 60
	v_readlane_b32 s23, v254, 61
	v_readlane_b32 s26, v255, 0
	v_readlane_b32 s27, v255, 1
	v_readlane_b32 s18, v254, 25
	v_readlane_b32 s19, v254, 26
	v_readlane_b32 s7, v255, 11
	s_add_u32 s84, s4, s6
	v_readlane_b32 s4, v254, 41
	v_readlane_b32 s14, v254, 52
	v_readlane_b32 s15, v254, 53
	v_readlane_b32 s12, v254, 45
	v_readlane_b32 s20, v254, 28
	v_readlane_b32 s18, v253, 38
	s_addc_u32 s85, s4, s7
	v_readlane_b32 s4, v253, 63
	v_readlane_b32 s6, v254, 3
	s_mov_b32 s15, 0x7fff0
	v_readlane_b32 s14, v254, 43
	v_readlane_b32 s8, v254, 42
	v_readlane_b32 s13, v254, 46
	v_readlane_b32 s21, v254, 29
	v_readlane_b32 s22, v254, 30
	v_readlane_b32 s23, v254, 31
	v_readlane_b32 s24, v254, 32
	v_readlane_b32 s25, v254, 33
	v_readlane_b32 s26, v254, 34
	v_readlane_b32 s27, v254, 35
	v_readlane_b32 s17, v254, 24
	v_readlane_b32 s19, v253, 39
	v_readlane_b32 s44, v253, 58
	s_mov_b32 s45, s4
	v_readlane_b32 s7, v254, 4
	v_readlane_b32 s86, v253, 0
	s_waitcnt lgkmcnt(0)
	s_nop 0
	v_readlane_b32 s5, v254, 0
	s_branch .LBB0_184

; #define WAIT_V0() asm volatile("s_waitcnt vmcnt(0)" ::: "memory")
; #define G_LANE_SETUP() \
;     int tid_ = threadIdx.x; \
;     asm volatile("" : "+v"(tid_));    \
;     const int wid = tid_ >> 6, lane = tid_ & 63, wr = wid >> 2, wc = wid & 3, fr = lane & 15, fq = lane >> 4; \
;     unsigned soff[4];        \
;     _Pragma("unroll") for (int i = 0; i < 4; ++i) { int sR, sC; stage_rc2(wid * 1024 + i * 8192 + lane * 16, sR, sC); soff[i] = (unsigned)(sR * K + sC) * 2u; }
; #define G_RDA(AF, buf, ks, mh) do { _Pragma("unroll") for (int m = 0; m < 4; ++m) AF[m] = *(const LDSP bf16x8*)(G_SA(buf) + aoff + ((mh) * 4 + m) * 2048 + (ks) * 1024); } while (0)
; #define G_SB0() __builtin_amdgcn_sched_barrier(0)
; template <int EK>
; DI void gemm_stream(const Params& p, int l, const bf16_t* __restrict__ A, const bf16_t* __restrict__ Bt, int M, int N, int K, ldsp_t shm) {
;     ...
;     const int nt = K / 64;
;     int pm, pn;
;     tile_coords(L, nM, nN, pm, pn);
;     const bf16_t* Ab = A + (size_t)pm * 256 * K;
;     const bf16_t* Bb = Bt + (size_t)pn * 256 * K;
;     { G_LANE_SETUP(); (void)wr; (void)wc; (void)fr; (void)fq; G_STAGE(Ab, Bb, 0, 0); WAIT_V0(); __syncthreads(); }
;     while (true) {
;         G_LANE_SETUP();
;         const int aoff = lds_byte2(wr * 128 + fr, fq * 8), boff = lds_byte2(wc * 64 + fr, fq * 8);
;         f32x4 acc[8][4];
; #pragma unroll
;         for (int m = 0; m < 8; ++m)
; #pragma unroll
;             for (int n = 0; n < 4; ++n) acc[m][n] = (f32x4){0.f, 0.f, 0.f, 0.f};
;         const int Ln = L + gridDim.x;
;         const bool has_next = Ln < nwg;
;         int pm2 = pm, pn2 = pn;
;         if (has_next) tile_coords(Ln, nM, nN, pm2, pn2);
;         const bf16_t* Ab2 = A + (size_t)pm2 * 256 * K;
;         const bf16_t* Bb2 = Bt + (size_t)pn2 * 256 * K;
;         bf16x8 Aa[4], Ab_[4], Bk0[4], Bk1[4];
;     ...
;         for (int t = 0; t < nt; ++t) {
;             const int cur = t & 1;
;             G_RDA(Aa, cur, 0, 0); G_RDB(Bk0, cur, 0);
;             if (t + 1 < nt) G_STAGE_B(Bb, cur ^ 1, t + 1);
;             else if (has_next) G_STAGE_B(Bb2, cur ^ 1, 0);
;             G_SB0();
;             if (t > 0) G_MMA(Ab_, Bk1, 1);
;             G_SB0();
;             if (t + 1 < nt) G_STAGE_A(Ab, cur ^ 1, t + 1);
;             else if (has_next) G_STAGE_A(Ab2, cur ^ 1, 0);
;             G_RDA(Ab_, cur, 0, 1);
.LBB0_190:
	v_lshlrev_b32_e32 v0, 4, v160
	v_and_b32_e32 v1, 32, v160
	v_bfe_u32 v161, v160, 2, 4
	v_and_b32_e32 v190, 64, v160
	v_bitop3_b32 v191, v0, v1, 48 bitop3:0x6c
	v_lshrrev_b32_e32 v2, 3, v160
	v_or_b32_e32 v1, v191, v190
	v_and_or_b32 v2, v2, s15, v161
	v_add_u32_e32 v200, 0x2000, v0
	v_lshl_or_b32 v192, v2, 13, v1
	v_lshrrev_b32_e32 v2, 7, v200
	v_and_or_b32 v2, v2, s15, v161
	v_add_u32_e32 v201, 0x4000, v0
	v_add_u32_e32 v221, 0x6000, v0
	v_and_b32_e32 v220, 0xfffffc00, v0
	v_lshl_or_b32 v194, v2, 13, v1
	v_lshrrev_b32_e32 v2, 7, v201
	v_lshrrev_b32_e32 v0, 7, v221
	v_and_or_b32 v2, v2, s15, v161
	v_and_or_b32 v0, v0, s15, v161
	v_lshl_or_b32 v196, v2, 13, v1
	v_lshl_or_b32 v198, v0, 13, v1
	v_lshlrev_b32_e32 v1, 6, v160
	v_lshlrev_b32_e32 v4, 2, v160
	v_and_b32_e32 v0, 48, v160
	v_and_b32_e32 v2, 0x3c0, v1
	v_and_b32_e32 v4, 32, v4
	v_bitop3_b32 v0, v2, v4, v0 bitop3:0x36
	s_movk_i32 s4, 0xc000
	v_and_or_b32 v218, v1, s4, v0
	s_add_u32 s4, s9, s50
	s_addc_u32 s5, s31, s51
	v_add_u32_e32 v34, 0x18000, v220
	v_lshl_add_u64 v[32:33], s[4:5], 0, v[192:193]
	v_readfirstlane_b32 s43, v34
	v_lshlrev_b32_e32 v3, 7, v160
	v_lshl_add_u64 v[32:33], v[32:33], 0, s[0:1]
	s_mov_b32 m0, s43
	v_mov_b32_e32 v195, v193
	v_add_u32_e32 v34, 0x1a000, v220
	v_and_or_b32 v219, v3, s28, v0
	global_load_lds_dwordx4 v[32:33], off
	v_lshl_add_u64 v[32:33], s[4:5], 0, v[194:195]
	v_readfirstlane_b32 s43, v34
	v_lshl_add_u64 v[32:33], v[32:33], 0, s[0:1]
	s_mov_b32 m0, s43
	v_mov_b32_e32 v197, v193
	v_add_u32_e32 v34, 0x1c000, v220
	global_load_lds_dwordx4 v[32:33], off
	v_lshl_add_u64 v[32:33], s[4:5], 0, v[196:197]
	v_readfirstlane_b32 s43, v34
	v_lshl_add_u64 v[32:33], v[32:33], 0, s[0:1]
	s_mov_b32 m0, s43
	v_mov_b32_e32 v199, v193
	v_add_u32_e32 v34, 0x1e000, v220
	global_load_lds_dwordx4 v[32:33], off
	v_lshl_add_u64 v[32:33], s[4:5], 0, v[198:199]
	v_readfirstlane_b32 s4, v34
	v_lshl_add_u64 v[32:33], v[32:33], 0, s[0:1]
	s_mov_b32 m0, s4
	s_nop 0
	global_load_lds_dwordx4 v[32:33], off
	s_add_u32 s4, s12, s6
	s_addc_u32 s5, s13, s7
	v_add_u32_e32 v34, 0x10000, v220
	v_lshl_add_u64 v[32:33], s[4:5], 0, v[192:193]
	v_readfirstlane_b32 s43, v34
	v_lshl_add_u64 v[32:33], v[32:33], 0, s[0:1]
	s_mov_b32 m0, s43
	v_add_u32_e32 v34, 0x12000, v220
	global_load_lds_dwordx4 v[32:33], off
	v_lshl_add_u64 v[32:33], s[4:5], 0, v[194:195]
	v_readfirstlane_b32 s43, v34
	v_lshl_add_u64 v[32:33], v[32:33], 0, s[0:1]
	s_mov_b32 m0, s43
	v_add_u32_e32 v34, 0x14000, v220
	global_load_lds_dwordx4 v[32:33], off
	v_lshl_add_u64 v[32:33], s[4:5], 0, v[196:197]
	v_readfirstlane_b32 s43, v34
	v_lshl_add_u64 v[32:33], v[32:33], 0, s[0:1]
	s_mov_b32 m0, s43
	v_add_u32_e32 v34, 0x16000, v220
	global_load_lds_dwordx4 v[32:33], off
	v_lshl_add_u64 v[32:33], s[4:5], 0, v[198:199]
	v_readfirstlane_b32 s4, v34
	v_lshl_add_u64 v[32:33], v[32:33], 0, s[0:1]
	s_mov_b32 m0, s4
	s_mov_b32 s43, 0x10000
	global_load_lds_dwordx4 v[32:33], off
	s_waitcnt vmcnt(8)
	s_barrier
; #define WAIT_V0() asm volatile("s_waitcnt vmcnt(0)" ::: "memory")
; #define G_STAGE_A(Ap, buf, kt) do { const char* ab_ = (const char*)(Ap) + (size_t)(kt) * 128; \
;       _Pragma("unroll") for (int i = 0; i < 4; ++i) \
;         __builtin_amdgcn_global_load_lds((const unsigned*)(ab_ + soff[i]), (LDSP unsigned*)(G_SA(buf) + wid * 1024 + i * 8192), 16, 0, 0); } while (0)
; #define G_STAGE_B(Bp, buf, kt) do { const char* bb_ = (const char*)(Bp) + (size_t)(kt) * 128; \
;       _Pragma("unroll") for (int i = 0; i < 4; ++i) \
;         __builtin_amdgcn_global_load_lds((const unsigned*)(bb_ + soff[i]), (LDSP unsigned*)(G_SB(buf) + wid * 1024 + i * 8192), 16, 0, 0); } while (0)
; #define G_RDA(AF, buf, ks, mh) do { _Pragma("unroll") for (int m = 0; m < 4; ++m) AF[m] = *(const LDSP bf16x8*)(G_SA(buf) + aoff + ((mh) * 4 + m) * 2048 + (ks) * 1024); } while (0)
; #define G_RDB(BF, buf, ks) do { _Pragma("unroll") for (int n = 0; n < 4; ++n) BF[n] = *(const LDSP bf16x8*)(G_SB(buf) + boff + n * 2048 + (ks) * 1024); } while (0)
; #define G_SB0() __builtin_amdgcn_sched_barrier(0)
; template <int EK>
; DI void gemm_stream(const Params& p, int l, const bf16_t* __restrict__ A, const bf16_t* __restrict__ Bt, int M, int N, int K, ldsp_t shm) {
;     ...
;         bf16x8 Aa[4], Ab_[4], Bk0[4], Bk1[4];
;     ...
;         for (int t = 0; t < nt; ++t) {
;             const int cur = t & 1;
;             G_RDA(Aa, cur, 0, 0); G_RDB(Bk0, cur, 0);
;             if (t + 1 < nt) G_STAGE_B(Bb, cur ^ 1, t + 1);
;             else if (has_next) G_STAGE_B(Bb2, cur ^ 1, 0);
;             G_SB0();
;             if (t > 0) G_MMA(Ab_, Bk1, 1);
;             G_SB0();
;             if (t + 1 < nt) G_STAGE_A(Ab, cur ^ 1, t + 1);
;             else if (has_next) G_STAGE_A(Ab2, cur ^ 1, 0);
;             G_RDA(Ab_, cur, 0, 1);
;             G_MMA(Aa, Bk0, 0); G_SB0();
;             G_RDA(Aa, cur, 1, 0); G_RDB(Bk1, cur, 1);
;             G_MMA(Ab_, Bk0, 1); G_SB0();
;             G_RDA(Ab_, cur, 1, 1);
;             G_MMA(Aa, Bk1, 0); G_SB0();
;             asm volatile("s_waitcnt lgkmcnt(0)" ::: "memory");
;             WAIT_V0(); __syncthreads();
;         }
;         G_MMA(Ab_, Bk1, 1);
	ds_read_b128 v[0:3], v218
	ds_read_b128 v[4:7], v218 offset:2048
	ds_read_b128 v[8:11], v218 offset:4096
	ds_read_b128 v[12:15], v218 offset:6144
	ds_read_b128 v[16:19], v219 offset:32768
	ds_read_b128 v[20:23], v219 offset:34816
	ds_read_b128 v[24:27], v219 offset:36864
	ds_read_b128 v[28:31], v219 offset:38912
	ds_read_b128 v[32:35], v218 offset:8192
	ds_read_b128 v[36:39], v218 offset:10240
	ds_read_b128 v[40:43], v218 offset:12288
	ds_read_b128 v[44:47], v218 offset:14336
	s_setprio 1
	s_waitcnt lgkmcnt(0)
	v_mfma_f32_16x16x32_bf16 v[48:51], v[16:19], v[0:3], 0
	v_mfma_f32_16x16x32_bf16 v[52:55], v[20:23], v[0:3], 0
	v_mfma_f32_16x16x32_bf16 v[56:59], v[24:27], v[0:3], 0
	v_mfma_f32_16x16x32_bf16 v[60:63], v[28:31], v[0:3], 0
	v_mfma_f32_16x16x32_bf16 v[162:165], v[16:19], v[4:7], 0
	v_mfma_f32_16x16x32_bf16 v[166:169], v[20:23], v[4:7], 0
	v_mfma_f32_16x16x32_bf16 v[170:173], v[24:27], v[4:7], 0
	v_mfma_f32_16x16x32_bf16 v[174:177], v[28:31], v[4:7], 0
	v_mfma_f32_16x16x32_bf16 v[178:181], v[16:19], v[8:11], 0
	v_mfma_f32_16x16x32_bf16 v[182:185], v[20:23], v[8:11], 0
	v_mfma_f32_16x16x32_bf16 v[186:189], v[24:27], v[8:11], 0
	v_mfma_f32_16x16x32_bf16 v[204:207], v[28:31], v[8:11], 0
	v_mfma_f32_16x16x32_bf16 v[210:213], v[16:19], v[12:15], 0
	v_mfma_f32_16x16x32_bf16 v[214:217], v[20:23], v[12:15], 0
	v_mfma_f32_16x16x32_bf16 v[222:225], v[24:27], v[12:15], 0
	v_mfma_f32_16x16x32_bf16 v[226:229], v[28:31], v[12:15], 0
	s_setprio 0
	ds_read_b128 v[12:15], v218 offset:1024
	ds_read_b128 v[230:233], v218 offset:3072
	ds_read_b128 v[234:237], v218 offset:5120
	ds_read_b128 v[238:241], v218 offset:7168
	ds_read_b128 v[64:67], v219 offset:33792
	ds_read_b128 v[68:71], v219 offset:35840
	ds_read_b128 v[72:75], v219 offset:37888
	ds_read_b128 v[76:79], v219 offset:39936
	s_setprio 1
	v_mfma_f32_16x16x32_bf16 v[140:143], v[16:19], v[32:35], 0
	v_mfma_f32_16x16x32_bf16 v[136:139], v[20:23], v[32:35], 0
	v_mfma_f32_16x16x32_bf16 v[132:135], v[24:27], v[32:35], 0
	v_mfma_f32_16x16x32_bf16 v[128:131], v[28:31], v[32:35], 0
	v_mfma_f32_16x16x32_bf16 v[124:127], v[16:19], v[36:39], 0
	v_mfma_f32_16x16x32_bf16 v[120:123], v[20:23], v[36:39], 0
	v_mfma_f32_16x16x32_bf16 v[116:119], v[24:27], v[36:39], 0
	v_mfma_f32_16x16x32_bf16 v[112:115], v[28:31], v[36:39], 0
	v_mfma_f32_16x16x32_bf16 v[108:111], v[16:19], v[40:43], 0
	v_mfma_f32_16x16x32_bf16 v[104:107], v[20:23], v[40:43], 0
	v_mfma_f32_16x16x32_bf16 v[100:103], v[24:27], v[40:43], 0
	v_mfma_f32_16x16x32_bf16 v[96:99], v[28:31], v[40:43], 0
	v_mfma_f32_16x16x32_bf16 v[92:95], v[16:19], v[44:47], 0
	v_mfma_f32_16x16x32_bf16 v[88:91], v[20:23], v[44:47], 0
	v_mfma_f32_16x16x32_bf16 v[84:87], v[24:27], v[44:47], 0
	v_mfma_f32_16x16x32_bf16 v[80:83], v[28:31], v[44:47], 0
	s_setprio 0
	ds_read_b128 v[156:159], v218 offset:9216
	ds_read_b128 v[152:155], v218 offset:11264
	ds_read_b128 v[148:151], v218 offset:13312
	ds_read_b128 v[144:147], v218 offset:15360
	s_setprio 1
	s_waitcnt lgkmcnt(0)
	v_mfma_f32_16x16x32_bf16 v[0:3], v[64:67], v[12:15], v[48:51]
	v_mfma_f32_16x16x32_bf16 v[4:7], v[68:71], v[12:15], v[52:55]
	v_mfma_f32_16x16x32_bf16 v[8:11], v[72:75], v[12:15], v[56:59]
	v_mfma_f32_16x16x32_bf16 v[12:15], v[76:79], v[12:15], v[60:63]
	v_mfma_f32_16x16x32_bf16 v[16:19], v[64:67], v[230:233], v[162:165]
	v_mfma_f32_16x16x32_bf16 v[20:23], v[68:71], v[230:233], v[166:169]
	v_mfma_f32_16x16x32_bf16 v[24:27], v[72:75], v[230:233], v[170:173]
	v_mfma_f32_16x16x32_bf16 v[28:31], v[76:79], v[230:233], v[174:177]
	v_mfma_f32_16x16x32_bf16 v[32:35], v[64:67], v[234:237], v[178:181]
	v_mfma_f32_16x16x32_bf16 v[36:39], v[68:71], v[234:237], v[182:185]
	v_mfma_f32_16x16x32_bf16 v[40:43], v[72:75], v[234:237], v[186:189]
	v_mfma_f32_16x16x32_bf16 v[44:47], v[76:79], v[234:237], v[204:207]
	v_mfma_f32_16x16x32_bf16 v[48:51], v[64:67], v[238:241], v[210:213]
	v_mfma_f32_16x16x32_bf16 v[52:55], v[68:71], v[238:241], v[214:217]
	v_mfma_f32_16x16x32_bf16 v[56:59], v[72:75], v[238:241], v[222:225]
	v_mfma_f32_16x16x32_bf16 v[60:63], v[76:79], v[238:241], v[226:229]
	s_setprio 0
	v_lshlrev_b32_e32 v160, 10, v160
	s_mov_b32 s47, 0xfffe0000
	v_lshlrev_b32_e32 v162, 6, v200
	v_lshlrev_b32_e32 v164, 6, v201
	v_lshlrev_b32_e32 v167, 6, v221
	v_and_or_b32 v160, v160, s47, v191
	v_lshlrev_b32_e32 v166, 13, v161
	s_add_u32 s4, s84, s50
	v_and_or_b32 v162, v162, s47, v191
	v_and_or_b32 v164, v164, s47, v191
	v_and_or_b32 v167, v167, s47, v191
	s_waitcnt lgkmcnt(0)
	v_or3_b32 v168, v160, v166, v190
	v_mov_b32_e32 v169, v193
	s_addc_u32 s5, s85, s51
	v_or3_b32 v170, v162, v166, v190
	v_mov_b32_e32 v171, v193
	v_or3_b32 v172, v164, v166, v190
	v_mov_b32_e32 v173, v193
	v_or3_b32 v174, v167, v166, v190
	v_mov_b32_e32 v175, v193
	s_waitcnt vmcnt(0)
	v_writelane_b32 v255, s52, 12
	v_writelane_b32 v255, s53, 13
	v_writelane_b32 v255, s64, 14
	v_writelane_b32 v255, s65, 15
	v_writelane_b32 v255, s30, 16
	s_mov_b64 s[64:65], s[4:5]
	s_add_u32 s4, s8, s6
	s_addc_u32 s5, s14, s7
	s_mov_b64 s[52:53], s[4:5]
	s_mov_b64 s[4:5], 0
	s_waitcnt vmcnt(0)
	v_lshrrev_b32_e32 v164, 6, v252
	v_lshlrev_b32_e32 v164, 10, v164
	s_nop 0
	v_readfirstlane_b32 s30, v164
	v_and_b32_e32 v165, 63, v252
	v_lshlrev_b32_e32 v165, 4, v165
	s_barrier
	s_and_b32 s6, s43, 0x10000
	v_add_u32_e32 v221, s6, v218
	v_or_b32_e32 v226, s6, v219
	s_xor_b32 s6, s6, 0x10000
	s_add_u32 s6, s6, s30
	.p2align	6
